# lazy rescale + row-max half exchange via v_permlane32_swap in attention + phase-0 tile loads de-serialized
# speedup vs baseline: 1.0335x; 1.0106x over previous
.LBB0_685:
	v_lshl_or_b32 v0, s38, 5, v202
	v_mad_u32_u24 v0, v0, s30, v208
	ds_read_b128 v[2:5], v0
	ds_read_b128 v[6:9], v0 offset:32
	s_waitcnt lgkmcnt(1)
	v_mfma_f32_32x32x16_bf16 v[80:95], v[2:5], v[148:151], 0
	s_waitcnt lgkmcnt(0)
	v_mfma_f32_32x32x16_bf16 v[80:95], v[6:9], v[96:99], v[80:95]
	ds_read_b128 v[2:5], v0 offset:64
	ds_read_b128 v[6:9], v0 offset:96
	s_waitcnt lgkmcnt(1)
	v_mfma_f32_32x32x16_bf16 v[80:95], v[2:5], v[100:103], v[80:95]
	s_waitcnt lgkmcnt(0)
	v_mfma_f32_32x32x16_bf16 v[80:95], v[6:9], v[104:107], v[80:95]
	ds_read_b128 v[2:5], v0 offset:128
	ds_read_b128 v[6:9], v0 offset:160
	s_waitcnt lgkmcnt(1)
	v_mfma_f32_32x32x16_bf16 v[80:95], v[2:5], v[108:111], v[80:95]
	s_waitcnt lgkmcnt(0)
	v_mfma_f32_32x32x16_bf16 v[80:95], v[6:9], v[112:115], v[80:95]
	ds_read_b128 v[2:5], v0 offset:192
	ds_read_b128 v[6:9], v0 offset:224
	s_waitcnt lgkmcnt(1)
	v_mfma_f32_32x32x16_bf16 v[80:95], v[2:5], v[116:119], v[80:95]
	s_waitcnt lgkmcnt(0)
	v_mfma_f32_32x32x16_bf16 v[80:95], v[6:9], v[120:123], v[80:95]
	ds_read_b128 v[2:5], v0 offset:256
	ds_read_b128 v[6:9], v0 offset:288
	s_waitcnt lgkmcnt(1)
	v_mfma_f32_32x32x16_bf16 v[80:95], v[2:5], v[124:127], v[80:95]
	s_waitcnt lgkmcnt(0)
	v_mfma_f32_32x32x16_bf16 v[80:95], v[6:9], v[128:131], v[80:95]
	ds_read_b128 v[2:5], v0 offset:320
	ds_read_b128 v[6:9], v0 offset:352
	s_waitcnt lgkmcnt(1)
	v_mfma_f32_32x32x16_bf16 v[80:95], v[2:5], v[132:135], v[80:95]
	s_waitcnt lgkmcnt(0)
	v_mfma_f32_32x32x16_bf16 v[80:95], v[6:9], v[140:143], v[80:95]
	s_nop 11
	v_max_f32_e32 v0, v81, v81
	v_max_f32_e32 v2, v80, v80
	v_max_f32_e32 v0, v2, v0
	v_max3_f32 v0, v0, v82, v83
	v_max3_f32 v0, v0, v84, v85
	v_max3_f32 v0, v0, v86, v87
	v_max3_f32 v0, v0, v88, v89
	v_max3_f32 v0, v0, v90, v91
	v_max3_f32 v0, v0, v92, v93
	v_max3_f32 v0, v0, v94, v95
	v_mov_b32_e32 v2, v0
	s_nop 1
	v_permlane32_swap_b32_e32 v2, v0
	s_waitcnt lgkmcnt(0)
	v_max_f32_e32 v2, v2, v2
	v_max_f32_e32 v0, v0, v2
	v_mul_f32_e32 v0, 0x3dd53b94, v0
	v_add_f32_e32 v250, 0xc1000000, v0
	v_cmp_gt_f32_e32 vcc, v250, v198
	s_cbranch_vccz .LBB0_684
	v_max_f32_e32 v0, v0, v0
	v_max_f32_e32 v2, v198, v198
	v_max_f32_e32 v2, v2, v0
	v_sub_f32_e32 v0, v198, v2
	v_exp_f32_e32 v0, v0
	v_mov_b32_e32 v198, v2
	v_pk_mul_f32 v[78:79], v[78:79], v[0:1] op_sel_hi:[1,0]
	v_pk_mul_f32 v[76:77], v[76:77], v[0:1] op_sel_hi:[1,0]
	v_pk_mul_f32 v[74:75], v[74:75], v[0:1] op_sel_hi:[1,0]
	v_pk_mul_f32 v[72:73], v[72:73], v[0:1] op_sel_hi:[1,0]
	v_pk_mul_f32 v[70:71], v[70:71], v[0:1] op_sel_hi:[1,0]
	v_pk_mul_f32 v[68:69], v[68:69], v[0:1] op_sel_hi:[1,0]
	v_pk_mul_f32 v[66:67], v[66:67], v[0:1] op_sel_hi:[1,0]
	v_pk_mul_f32 v[64:65], v[64:65], v[0:1] op_sel_hi:[1,0]
	v_pk_mul_f32 v[62:63], v[62:63], v[0:1] op_sel_hi:[1,0]
	v_pk_mul_f32 v[60:61], v[60:61], v[0:1] op_sel_hi:[1,0]
	v_pk_mul_f32 v[58:59], v[58:59], v[0:1] op_sel_hi:[1,0]
	v_pk_mul_f32 v[56:57], v[56:57], v[0:1] op_sel_hi:[1,0]
	v_pk_mul_f32 v[54:55], v[54:55], v[0:1] op_sel_hi:[1,0]
	v_pk_mul_f32 v[52:53], v[52:53], v[0:1] op_sel_hi:[1,0]
	v_pk_mul_f32 v[50:51], v[50:51], v[0:1] op_sel_hi:[1,0]
	v_pk_mul_f32 v[48:49], v[48:49], v[0:1] op_sel_hi:[1,0]
	v_pk_mul_f32 v[46:47], v[46:47], v[0:1] op_sel_hi:[1,0]
	v_pk_mul_f32 v[44:45], v[44:45], v[0:1] op_sel_hi:[1,0]
	v_pk_mul_f32 v[42:43], v[42:43], v[0:1] op_sel_hi:[1,0]
	v_pk_mul_f32 v[40:41], v[40:41], v[0:1] op_sel_hi:[1,0]
	v_pk_mul_f32 v[38:39], v[38:39], v[0:1] op_sel_hi:[1,0]
	v_pk_mul_f32 v[36:37], v[36:37], v[0:1] op_sel_hi:[1,0]
	v_pk_mul_f32 v[34:35], v[34:35], v[0:1] op_sel_hi:[1,0]
	v_pk_mul_f32 v[32:33], v[32:33], v[0:1] op_sel_hi:[1,0]
	v_pk_mul_f32 v[30:31], v[30:31], v[0:1] op_sel_hi:[1,0]
	v_pk_mul_f32 v[28:29], v[28:29], v[0:1] op_sel_hi:[1,0]
	v_pk_mul_f32 v[26:27], v[26:27], v[0:1] op_sel_hi:[1,0]
	v_pk_mul_f32 v[24:25], v[24:25], v[0:1] op_sel_hi:[1,0]
	v_pk_mul_f32 v[22:23], v[22:23], v[0:1] op_sel_hi:[1,0]
	v_pk_mul_f32 v[20:21], v[20:21], v[0:1] op_sel_hi:[1,0]
	v_pk_mul_f32 v[18:19], v[18:19], v[0:1] op_sel_hi:[1,0]
	v_pk_mul_f32 v[16:17], v[16:17], v[0:1] op_sel_hi:[1,0]
	v_mul_f32_e32 v193, v193, v0
	s_branch .LBB0_684

.LBB0_1022:
	ds_read_b128 v[2:5], v193
	ds_read_b128 v[6:9], v193 offset:32
	s_waitcnt lgkmcnt(1)
	v_mfma_f32_32x32x16_bf16 v[80:95], v[2:5], v[96:99], 0
	s_waitcnt lgkmcnt(0)
	v_mfma_f32_32x32x16_bf16 v[80:95], v[6:9], v[100:103], v[80:95]
	ds_read_b128 v[2:5], v193 offset:64
	ds_read_b128 v[6:9], v193 offset:96
	s_waitcnt lgkmcnt(1)
	v_mfma_f32_32x32x16_bf16 v[80:95], v[2:5], v[104:107], v[80:95]
	s_waitcnt lgkmcnt(0)
	v_mfma_f32_32x32x16_bf16 v[80:95], v[6:9], v[108:111], v[80:95]
	s_nop 11
	v_max_f32_e32 v1, v81, v81
	v_max_f32_e32 v2, v80, v80
	v_max_f32_e32 v1, v2, v1
	v_max3_f32 v1, v1, v82, v83
	v_max3_f32 v1, v1, v84, v85
	v_max3_f32 v1, v1, v86, v87
	v_max3_f32 v1, v1, v88, v89
	v_max3_f32 v1, v1, v90, v91
	v_max3_f32 v1, v1, v92, v93
	v_max3_f32 v1, v1, v94, v95
	v_mov_b32_e32 v2, v1
	s_nop 1
	v_permlane32_swap_b32_e32 v2, v1
	s_waitcnt lgkmcnt(0)
	v_max_f32_e32 v2, v2, v2
	v_max_f32_e32 v1, v1, v2
	v_mul_f32_e32 v1, 0x3e38aa3b, v1
	v_add_f32_e32 v250, 0xc1000000, v1
	v_cmp_gt_f32_e32 vcc, v250, v180
	s_cbranch_vccz .LBB0_1024
	v_max_f32_e32 v1, v1, v1
	v_max_f32_e32 v2, v180, v180
	v_max_f32_e32 v1, v2, v1
	v_sub_f32_e32 v2, v180, v1
	v_exp_f32_e32 v2, v2
	v_mov_b32_e32 v180, v1
	v_pk_mul_f32 v[78:79], v[78:79], v[2:3] op_sel_hi:[1,0]
	v_pk_mul_f32 v[76:77], v[76:77], v[2:3] op_sel_hi:[1,0]
	v_pk_mul_f32 v[74:75], v[74:75], v[2:3] op_sel_hi:[1,0]
	v_pk_mul_f32 v[72:73], v[72:73], v[2:3] op_sel_hi:[1,0]
	v_pk_mul_f32 v[70:71], v[70:71], v[2:3] op_sel_hi:[1,0]
	v_pk_mul_f32 v[68:69], v[68:69], v[2:3] op_sel_hi:[1,0]
	v_pk_mul_f32 v[66:67], v[66:67], v[2:3] op_sel_hi:[1,0]
	v_pk_mul_f32 v[64:65], v[64:65], v[2:3] op_sel_hi:[1,0]
	v_pk_mul_f32 v[62:63], v[62:63], v[2:3] op_sel_hi:[1,0]
	v_pk_mul_f32 v[60:61], v[60:61], v[2:3] op_sel_hi:[1,0]
	v_pk_mul_f32 v[58:59], v[58:59], v[2:3] op_sel_hi:[1,0]
	v_pk_mul_f32 v[56:57], v[56:57], v[2:3] op_sel_hi:[1,0]
	v_pk_mul_f32 v[54:55], v[54:55], v[2:3] op_sel_hi:[1,0]
	v_pk_mul_f32 v[52:53], v[52:53], v[2:3] op_sel_hi:[1,0]
	v_pk_mul_f32 v[50:51], v[50:51], v[2:3] op_sel_hi:[1,0]
	v_pk_mul_f32 v[48:49], v[48:49], v[2:3] op_sel_hi:[1,0]
	v_pk_mul_f32 v[46:47], v[46:47], v[2:3] op_sel_hi:[1,0]
	v_pk_mul_f32 v[44:45], v[44:45], v[2:3] op_sel_hi:[1,0]
	v_pk_mul_f32 v[42:43], v[42:43], v[2:3] op_sel_hi:[1,0]
	v_pk_mul_f32 v[40:41], v[40:41], v[2:3] op_sel_hi:[1,0]
	v_pk_mul_f32 v[38:39], v[38:39], v[2:3] op_sel_hi:[1,0]
	v_pk_mul_f32 v[36:37], v[36:37], v[2:3] op_sel_hi:[1,0]
	v_pk_mul_f32 v[34:35], v[34:35], v[2:3] op_sel_hi:[1,0]
	v_pk_mul_f32 v[32:33], v[32:33], v[2:3] op_sel_hi:[1,0]
	v_pk_mul_f32 v[30:31], v[30:31], v[2:3] op_sel_hi:[1,0]
	v_pk_mul_f32 v[28:29], v[28:29], v[2:3] op_sel_hi:[1,0]
	v_pk_mul_f32 v[26:27], v[26:27], v[2:3] op_sel_hi:[1,0]
	v_pk_mul_f32 v[24:25], v[24:25], v[2:3] op_sel_hi:[1,0]
	v_pk_mul_f32 v[22:23], v[22:23], v[2:3] op_sel_hi:[1,0]
	v_pk_mul_f32 v[20:21], v[20:21], v[2:3] op_sel_hi:[1,0]
	v_pk_mul_f32 v[18:19], v[18:19], v[2:3] op_sel_hi:[1,0]
	v_pk_mul_f32 v[16:17], v[16:17], v[2:3] op_sel_hi:[1,0]
	v_mul_f32_e32 v196, v196, v2

.LBB0_1297:
	s_barrier
	s_waitcnt vmcnt(3)
	ds_write_b128 v166, v[112:115]
	s_waitcnt vmcnt(2)
	ds_write_b128 v166, v[116:119] offset:4352
	s_waitcnt vmcnt(1)
	ds_write_b128 v166, v[120:123] offset:8704
	s_waitcnt vmcnt(0)
	ds_write_b128 v166, v[124:127] offset:13056
	s_waitcnt vmcnt(1)
	ds_write_b128 v167, v[140:143] offset:17408
	ds_write_b128 v167, v[132:135] offset:22016
	ds_write_b128 v167, v[128:131] offset:26624
	s_waitcnt vmcnt(0)
	ds_write_b128 v167, v[136:139] offset:31232
	s_waitcnt lgkmcnt(0)
	s_barrier
	ds_read_b128 v[64:67], v170
	ds_read_b128 v[112:115], v170 offset:32
	s_waitcnt lgkmcnt(1)
	v_mfma_f32_32x32x16_bf16 v[64:79], v[64:67], v[108:111], 0
	v_lshl_add_u64 v[124:125], s[14:15], 0, v[162:163]
	v_add_co_u32_e32 v178, vcc, s37, v124
	v_lshl_add_u64 v[126:127], s[14:15], 0, v[154:155]
	s_nop 0
	v_addc_co_u32_e32 v179, vcc, 0, v125, vcc
	v_add_co_u32_e32 v180, vcc, s38, v124
	s_waitcnt lgkmcnt(0)
	v_mfma_f32_32x32x16_bf16 v[64:79], v[112:115], v[104:107], v[64:79]
	ds_read_b128 v[112:115], v170 offset:64
	ds_read_b128 v[116:119], v170 offset:96
	v_lshl_add_u64 v[128:129], s[14:15], 0, v[156:157]
	v_lshl_add_u64 v[130:131], s[14:15], 0, v[158:159]
	v_lshl_add_u64 v[136:137], s[14:15], 0, v[160:161]
	v_addc_co_u32_e32 v181, vcc, 0, v125, vcc
	v_add_co_u32_e32 v182, vcc, s39, v124
	s_waitcnt lgkmcnt(1)
	v_mfma_f32_32x32x16_bf16 v[64:79], v[112:115], v[100:103], v[64:79]
	ds_read_b128 v[112:115], v170 offset:128
	v_addc_co_u32_e32 v183, vcc, 0, v125, vcc
	v_add_co_u32_e32 v124, vcc, s40, v124
	s_nop 1
	v_addc_co_u32_e32 v125, vcc, 0, v125, vcc
	s_waitcnt lgkmcnt(1)
	v_mfma_f32_32x32x16_bf16 v[64:79], v[116:119], v[96:99], v[64:79]
	ds_read_b128 v[116:119], v170 offset:160
	ds_read_b128 v[120:123], v170 offset:192
	ds_read_b128 v[174:177], v170 offset:224
	s_waitcnt lgkmcnt(3)
	v_mfma_f32_32x32x16_bf16 v[64:79], v[112:115], v[92:95], v[64:79]
	s_waitcnt lgkmcnt(2)
	v_mfma_f32_32x32x16_bf16 v[64:79], v[116:119], v[88:91], v[64:79]
	global_load_dwordx4 v[140:143], v[126:127], off
	global_load_dwordx4 v[132:135], v[128:129], off
	s_nop 0
	global_load_dwordx4 v[128:131], v[130:131], off
	s_nop 0
	global_load_dwordx4 v[136:139], v[136:137], off
	s_nop 0
	global_load_dwordx4 v[112:115], v[178:179], off
	global_load_dwordx4 v[116:119], v[180:181], off
	s_waitcnt lgkmcnt(1)
	v_mfma_f32_32x32x16_bf16 v[64:79], v[120:123], v[84:87], v[64:79]
	global_load_dwordx4 v[120:123], v[182:183], off
	s_nop 0
	global_load_dwordx4 v[124:127], v[124:125], off
	s_waitcnt lgkmcnt(0)
	v_mfma_f32_32x32x16_bf16 v[64:79], v[174:177], v[80:83], v[64:79]
	s_nop 11
	v_max_f32_e32 v152, v65, v65
	v_max_f32_e32 v173, v64, v64
	v_max_f32_e32 v152, v173, v152
	v_max3_f32 v152, v152, v66, v67
	v_max3_f32 v152, v152, v68, v69
	v_max3_f32 v152, v152, v70, v71
	v_max3_f32 v152, v152, v72, v73
	v_max3_f32 v152, v152, v74, v75
	v_max3_f32 v152, v152, v76, v77
	v_max3_f32 v152, v152, v78, v79
	v_mov_b32_e32 v173, v152
	s_nop 1
	v_permlane32_swap_b32_e32 v173, v152
	s_waitcnt lgkmcnt(0)
	v_max_f32_e32 v173, v173, v173
	v_max_f32_e32 v152, v152, v173
	v_mul_f32_e32 v152, 0x3e0293ee, v152
	v_add_f32_e32 v250, 0xc1000000, v152
	v_cmp_gt_f32_e32 vcc, v250, v153
	s_cbranch_vccz .LBB0_1299
	v_max_f32_e32 v152, v152, v152
	v_max_f32_e32 v173, v153, v153
	v_max_f32_e32 v173, v173, v152
	v_sub_f32_e32 v152, v153, v173
	v_exp_f32_e32 v152, v152
	s_nop 0
	v_pk_mul_f32 v[62:63], v[62:63], v[152:153] op_sel_hi:[1,0]
	v_pk_mul_f32 v[60:61], v[60:61], v[152:153] op_sel_hi:[1,0]
	v_pk_mul_f32 v[58:59], v[58:59], v[152:153] op_sel_hi:[1,0]
	v_pk_mul_f32 v[56:57], v[56:57], v[152:153] op_sel_hi:[1,0]
	v_pk_mul_f32 v[54:55], v[54:55], v[152:153] op_sel_hi:[1,0]
	v_pk_mul_f32 v[52:53], v[52:53], v[152:153] op_sel_hi:[1,0]
	v_pk_mul_f32 v[50:51], v[50:51], v[152:153] op_sel_hi:[1,0]
	v_pk_mul_f32 v[48:49], v[48:49], v[152:153] op_sel_hi:[1,0]
	v_pk_mul_f32 v[46:47], v[46:47], v[152:153] op_sel_hi:[1,0]
	v_pk_mul_f32 v[44:45], v[44:45], v[152:153] op_sel_hi:[1,0]
	v_pk_mul_f32 v[42:43], v[42:43], v[152:153] op_sel_hi:[1,0]
	v_pk_mul_f32 v[40:41], v[40:41], v[152:153] op_sel_hi:[1,0]
	v_pk_mul_f32 v[38:39], v[38:39], v[152:153] op_sel_hi:[1,0]
	v_pk_mul_f32 v[36:37], v[36:37], v[152:153] op_sel_hi:[1,0]
	v_pk_mul_f32 v[34:35], v[34:35], v[152:153] op_sel_hi:[1,0]
	v_pk_mul_f32 v[32:33], v[32:33], v[152:153] op_sel_hi:[1,0]
	v_pk_mul_f32 v[30:31], v[30:31], v[152:153] op_sel_hi:[1,0]
	v_pk_mul_f32 v[28:29], v[28:29], v[152:153] op_sel_hi:[1,0]
	v_pk_mul_f32 v[26:27], v[26:27], v[152:153] op_sel_hi:[1,0]
	v_pk_mul_f32 v[24:25], v[24:25], v[152:153] op_sel_hi:[1,0]
	v_pk_mul_f32 v[22:23], v[22:23], v[152:153] op_sel_hi:[1,0]
	v_pk_mul_f32 v[20:21], v[20:21], v[152:153] op_sel_hi:[1,0]
	v_pk_mul_f32 v[18:19], v[18:19], v[152:153] op_sel_hi:[1,0]
	v_pk_mul_f32 v[16:17], v[16:17], v[152:153] op_sel_hi:[1,0]
	v_pk_mul_f32 v[14:15], v[14:15], v[152:153] op_sel_hi:[1,0]
	v_pk_mul_f32 v[12:13], v[12:13], v[152:153] op_sel_hi:[1,0]
	v_pk_mul_f32 v[10:11], v[10:11], v[152:153] op_sel_hi:[1,0]
	v_pk_mul_f32 v[8:9], v[8:9], v[152:153] op_sel_hi:[1,0]
	v_pk_mul_f32 v[6:7], v[6:7], v[152:153] op_sel_hi:[1,0]
	v_pk_mul_f32 v[4:5], v[4:5], v[152:153] op_sel_hi:[1,0]
	v_pk_mul_f32 v[2:3], v[2:3], v[152:153] op_sel_hi:[1,0]
	v_pk_mul_f32 v[0:1], v[0:1], v[152:153] op_sel_hi:[1,0]
	v_mul_f32_e32 v172, v172, v152
	v_mov_b32_e32 v153, v173
.LBB0_1299:
	v_mov_b32_e32 v152, v153
	v_pk_fma_f32 v[64:65], v[64:65], s[18:19], v[152:153] op_sel_hi:[1,0,0] neg_lo:[0,0,1] neg_hi:[0,0,1]
	v_pk_fma_f32 v[72:73], v[72:73], s[18:19], v[152:153] op_sel_hi:[1,0,0] neg_lo:[0,0,1] neg_hi:[0,0,1]
	v_exp_f32_e32 v202, v64
	v_exp_f32_e32 v203, v65
	v_pk_fma_f32 v[64:65], v[66:67], s[18:19], v[152:153] op_sel_hi:[1,0,0] neg_lo:[0,0,1] neg_hi:[0,0,1]
	ds_read_b128 v[174:177], v171 offset:17440
	v_exp_f32_e32 v204, v64
	v_exp_f32_e32 v205, v65
	v_pk_fma_f32 v[64:65], v[68:69], s[18:19], v[152:153] op_sel_hi:[1,0,0] neg_lo:[0,0,1] neg_hi:[0,0,1]
	v_pk_fma_f32 v[68:69], v[70:71], s[18:19], v[152:153] op_sel_hi:[1,0,0] neg_lo:[0,0,1] neg_hi:[0,0,1]
	v_exp_f32_e32 v206, v64
	v_exp_f32_e32 v207, v65
	ds_read_b128 v[64:67], v171 offset:17408
	v_exp_f32_e32 v208, v68
	v_exp_f32_e32 v209, v69
	v_cvt_pk_bf16_f32 v68, v202, v203
	v_cvt_pk_bf16_f32 v69, v204, v205
	v_cvt_pk_bf16_f32 v70, v206, v207
	v_cvt_pk_bf16_f32 v71, v208, v209
	v_exp_f32_e32 v210, v72
	v_exp_f32_e32 v211, v73
	s_waitcnt lgkmcnt(0)
	v_mfma_f32_32x32x16_bf16 v[48:63], v[64:67], v[68:71], v[48:63]
	ds_read_b128 v[64:67], v171 offset:22016
	ds_read_b128 v[178:181], v171 offset:22048
	s_waitcnt lgkmcnt(1)
	v_mfma_f32_32x32x16_bf16 v[32:47], v[64:67], v[68:71], v[32:47]
	ds_read_b128 v[64:67], v171 offset:26624
	ds_read_b128 v[182:185], v171 offset:31232
	ds_read_b128 v[186:189], v171 offset:26656
	ds_read_b128 v[190:193], v171 offset:31264
	s_waitcnt lgkmcnt(3)
	v_mfma_f32_32x32x16_bf16 v[16:31], v[64:67], v[68:71], v[16:31]
	v_fma_f32 v64, v74, s18, -v152
	v_fma_f32 v65, v75, s18, -v152
	v_exp_f32_e32 v212, v64
	v_exp_f32_e32 v213, v65
	v_pk_fma_f32 v[64:65], v[76:77], s[18:19], v[152:153] op_sel_hi:[1,0,0] neg_lo:[0,0,1] neg_hi:[0,0,1]
	s_nop 0
	v_exp_f32_e32 v214, v64
	v_exp_f32_e32 v215, v65
	v_pk_fma_f32 v[64:65], v[78:79], s[18:19], v[152:153] op_sel_hi:[1,0,0] neg_lo:[0,0,1] neg_hi:[0,0,1]
	s_waitcnt lgkmcnt(2)
	v_mfma_f32_32x32x16_bf16 v[0:15], v[182:185], v[68:71], v[0:15]
	v_exp_f32_e32 v216, v64
	v_exp_f32_e32 v217, v65
	v_cvt_pk_bf16_f32 v182, v210, v211
	v_cvt_pk_bf16_f32 v183, v212, v213
	v_cvt_pk_bf16_f32 v184, v214, v215
	v_cvt_pk_bf16_f32 v185, v216, v217
	s_nop 1
	v_mfma_f32_32x32x16_bf16 v[48:63], v[174:177], v[182:185], v[48:63]
	ds_read_b128 v[64:67], v170 offset:8704
	ds_read_b128 v[174:177], v170 offset:8736
	s_waitcnt lgkmcnt(1)
	v_mfma_f32_32x32x16_bf16 v[64:79], v[64:67], v[108:111], 0
	s_waitcnt lgkmcnt(0)
	v_mfma_f32_32x32x16_bf16 v[64:79], v[174:177], v[104:107], v[64:79]
	ds_read_b128 v[174:177], v170 offset:8768
	ds_read_b128 v[194:197], v170 offset:8800
	s_waitcnt lgkmcnt(1)
	v_mfma_f32_32x32x16_bf16 v[64:79], v[174:177], v[100:103], v[64:79]
	s_waitcnt lgkmcnt(0)
	v_mfma_f32_32x32x16_bf16 v[64:79], v[194:197], v[96:99], v[64:79]
	ds_read_b128 v[174:177], v170 offset:8832
	ds_read_b128 v[194:197], v170 offset:8864
	s_waitcnt lgkmcnt(1)
	v_mfma_f32_32x32x16_bf16 v[64:79], v[174:177], v[92:95], v[64:79]
	s_waitcnt lgkmcnt(0)
	v_mfma_f32_32x32x16_bf16 v[64:79], v[194:197], v[88:91], v[64:79]
	ds_read_b128 v[174:177], v170 offset:8896
	ds_read_b128 v[194:197], v170 offset:8928
	s_waitcnt lgkmcnt(1)
	v_mfma_f32_32x32x16_bf16 v[64:79], v[174:177], v[84:87], v[64:79]
	v_add_f32_e64 v174, v202, 0
	v_add_f32_e64 v175, v203, 0
	v_add_f32_e64 v174, v204, v174
	v_add_f32_e64 v175, v205, v175
	v_add_f32_e64 v174, v206, v174
	v_add_f32_e64 v175, v207, v175
	v_pk_add_f32 v[174:175], v[208:209], v[174:175]
	s_waitcnt lgkmcnt(0)
	v_mfma_f32_32x32x16_bf16 v[64:79], v[194:197], v[80:83], v[64:79]
	v_add_f32_e64 v174, v210, v174
	v_add_f32_e64 v175, v211, v175
	v_add_f32_e64 v174, v212, v174
	v_add_f32_e64 v175, v213, v175
	v_add_f32_e64 v174, v214, v174
	v_add_f32_e64 v175, v215, v175
	s_nop 5
	v_max_f32_e32 v152, v65, v65
	v_max_f32_e32 v173, v64, v64
	v_max_f32_e32 v152, v173, v152
	v_max3_f32 v152, v152, v66, v67
	v_max3_f32 v152, v152, v68, v69
	v_max3_f32 v152, v152, v70, v71
	v_max3_f32 v152, v152, v72, v73
	v_max3_f32 v152, v152, v74, v75
	v_max3_f32 v152, v152, v76, v77
	v_max3_f32 v152, v152, v78, v79
	v_mov_b32_e32 v173, v152
	s_nop 1
	v_permlane32_swap_b32_e32 v173, v152
	v_mfma_f32_32x32x16_bf16 v[32:47], v[178:181], v[182:185], v[32:47]
	v_add_f32_e64 v174, v216, v174
	v_add_f32_e64 v175, v217, v175
	s_waitcnt lgkmcnt(0)
	v_max_f32_e32 v173, v173, v173
	v_max_f32_e32 v152, v152, v173
	v_add_f32_e32 v174, v174, v175
	v_mul_f32_e32 v152, 0x3e0293ee, v152
	v_mfma_f32_32x32x16_bf16 v[16:31], v[186:189], v[182:185], v[16:31]
	v_add_f32_e32 v172, v172, v174
	v_add_f32_e32 v250, 0xc1000000, v152
	v_cmp_gt_f32_e32 vcc, v250, v153
	v_mfma_f32_32x32x16_bf16 v[0:15], v[190:193], v[182:185], v[0:15]
	s_cbranch_vccnz .LBB0_1295
	v_mov_b32_e32 v152, v153
	s_branch .LBB0_1296
.LBB0_1301:
	s_barrier
	s_waitcnt vmcnt(3)
	ds_write_b128 v166, v[112:115]
	s_waitcnt vmcnt(2)
	ds_write_b128 v166, v[116:119] offset:4352
	s_waitcnt vmcnt(1)
	ds_write_b128 v166, v[120:123] offset:8704
	s_waitcnt vmcnt(0)
	ds_write_b128 v166, v[124:127] offset:13056
	ds_write_b128 v167, v[140:143] offset:17408
	ds_write_b128 v167, v[132:135] offset:22016
	ds_write_b128 v167, v[128:131] offset:26624
	ds_write_b128 v167, v[136:139] offset:31232
	s_waitcnt lgkmcnt(0)
	s_barrier
	ds_read_b128 v[64:67], v170
	ds_read_b128 v[112:115], v170 offset:32
	s_waitcnt lgkmcnt(1)
	v_mfma_f32_32x32x16_bf16 v[64:79], v[64:67], v[108:111], 0
	s_waitcnt lgkmcnt(0)
	v_mfma_f32_32x32x16_bf16 v[64:79], v[112:115], v[104:107], v[64:79]
	ds_read_b128 v[112:115], v170 offset:64
	ds_read_b128 v[116:119], v170 offset:96
	s_waitcnt lgkmcnt(1)
	v_mfma_f32_32x32x16_bf16 v[64:79], v[112:115], v[100:103], v[64:79]
	s_waitcnt lgkmcnt(0)
	v_mfma_f32_32x32x16_bf16 v[64:79], v[116:119], v[96:99], v[64:79]
	ds_read_b128 v[112:115], v170 offset:128
	ds_read_b128 v[116:119], v170 offset:160
	s_waitcnt lgkmcnt(1)
	v_mfma_f32_32x32x16_bf16 v[64:79], v[112:115], v[92:95], v[64:79]
	s_waitcnt lgkmcnt(0)
	v_mfma_f32_32x32x16_bf16 v[64:79], v[116:119], v[88:91], v[64:79]
	ds_read_b128 v[112:115], v170 offset:192
	ds_read_b128 v[116:119], v170 offset:224
	s_waitcnt lgkmcnt(1)
	v_mfma_f32_32x32x16_bf16 v[64:79], v[112:115], v[84:87], v[64:79]
	s_waitcnt lgkmcnt(0)
	v_mfma_f32_32x32x16_bf16 v[64:79], v[116:119], v[80:83], v[64:79]
	s_nop 11
	v_max_f32_e32 v112, v65, v65
	v_max_f32_e32 v113, v64, v64
	v_max_f32_e32 v112, v113, v112
	v_max3_f32 v112, v112, v66, v67
	v_max3_f32 v112, v112, v68, v69
	v_max3_f32 v112, v112, v70, v71
	v_max3_f32 v112, v112, v72, v73
	v_max3_f32 v112, v112, v74, v75
	v_max3_f32 v112, v112, v76, v77
	v_max3_f32 v112, v112, v78, v79
	v_mov_b32_e32 v113, v112
	s_nop 1
	v_permlane32_swap_b32_e32 v113, v112
	s_waitcnt lgkmcnt(0)
	v_max_f32_e32 v113, v113, v113
	v_max_f32_e32 v112, v112, v113
	v_mul_f32_e32 v112, 0x3e0293ee, v112
	v_add_f32_e32 v250, 0xc1000000, v112
	v_cmp_gt_f32_e32 vcc, v250, v153
	s_cbranch_vccz .LBB0_1303
	v_max_f32_e32 v112, v112, v112
	v_max_f32_e32 v113, v153, v153
	v_max_f32_e32 v152, v113, v112
	v_sub_f32_e32 v112, v153, v152
	v_exp_f32_e32 v112, v112
	v_mov_b32_e32 v153, v152
	v_pk_mul_f32 v[62:63], v[62:63], v[112:113] op_sel_hi:[1,0]
	v_pk_mul_f32 v[60:61], v[60:61], v[112:113] op_sel_hi:[1,0]
	v_pk_mul_f32 v[58:59], v[58:59], v[112:113] op_sel_hi:[1,0]
	v_pk_mul_f32 v[56:57], v[56:57], v[112:113] op_sel_hi:[1,0]
	v_pk_mul_f32 v[54:55], v[54:55], v[112:113] op_sel_hi:[1,0]
	v_pk_mul_f32 v[52:53], v[52:53], v[112:113] op_sel_hi:[1,0]
	v_pk_mul_f32 v[50:51], v[50:51], v[112:113] op_sel_hi:[1,0]
	v_pk_mul_f32 v[48:49], v[48:49], v[112:113] op_sel_hi:[1,0]
	v_pk_mul_f32 v[46:47], v[46:47], v[112:113] op_sel_hi:[1,0]
	v_pk_mul_f32 v[44:45], v[44:45], v[112:113] op_sel_hi:[1,0]
	v_pk_mul_f32 v[42:43], v[42:43], v[112:113] op_sel_hi:[1,0]
	v_pk_mul_f32 v[40:41], v[40:41], v[112:113] op_sel_hi:[1,0]
	v_pk_mul_f32 v[38:39], v[38:39], v[112:113] op_sel_hi:[1,0]
	v_pk_mul_f32 v[36:37], v[36:37], v[112:113] op_sel_hi:[1,0]
	v_pk_mul_f32 v[34:35], v[34:35], v[112:113] op_sel_hi:[1,0]
	v_pk_mul_f32 v[32:33], v[32:33], v[112:113] op_sel_hi:[1,0]
	v_pk_mul_f32 v[30:31], v[30:31], v[112:113] op_sel_hi:[1,0]
	v_pk_mul_f32 v[28:29], v[28:29], v[112:113] op_sel_hi:[1,0]
	v_pk_mul_f32 v[26:27], v[26:27], v[112:113] op_sel_hi:[1,0]
	v_pk_mul_f32 v[24:25], v[24:25], v[112:113] op_sel_hi:[1,0]
	v_pk_mul_f32 v[22:23], v[22:23], v[112:113] op_sel_hi:[1,0]
	v_pk_mul_f32 v[20:21], v[20:21], v[112:113] op_sel_hi:[1,0]
	v_pk_mul_f32 v[18:19], v[18:19], v[112:113] op_sel_hi:[1,0]
	v_pk_mul_f32 v[16:17], v[16:17], v[112:113] op_sel_hi:[1,0]
	v_pk_mul_f32 v[14:15], v[14:15], v[112:113] op_sel_hi:[1,0]
	v_pk_mul_f32 v[12:13], v[12:13], v[112:113] op_sel_hi:[1,0]
	v_pk_mul_f32 v[10:11], v[10:11], v[112:113] op_sel_hi:[1,0]
	v_pk_mul_f32 v[8:9], v[8:9], v[112:113] op_sel_hi:[1,0]
	v_pk_mul_f32 v[6:7], v[6:7], v[112:113] op_sel_hi:[1,0]
	v_pk_mul_f32 v[4:5], v[4:5], v[112:113] op_sel_hi:[1,0]
	v_pk_mul_f32 v[2:3], v[2:3], v[112:113] op_sel_hi:[1,0]
	v_pk_mul_f32 v[0:1], v[0:1], v[112:113] op_sel_hi:[1,0]
	v_mul_f32_e32 v172, v172, v112
	v_mov_b32_e32 v112, v152
	s_branch .LBB0_1304
